# P5 gate epilogue: both bias vector pairs loaded once up front; the three mid-epilogue load+vmcnt(0) drains (which also waited on write-through store acks) removed
# baseline (speedup 1.0000x reference)
; __device__ __forceinline__ unsigned cvt_pk_bf16(float lo, float hi) { unsigned r; asm("v_cvt_pk_bf16_f32 %0, %1, %2" : "=v"(r) : "v"(lo), "v"(hi)); return r; }
; __device__ __forceinline__ float sigmoidf_(float x) { return __builtin_amdgcn_rcpf(1.0f + __expf(-x)); }
;     __device__ __forceinline__ void operator()(f32x4 (&acc)[2][2][4][2], const GUnit& u, int wr, int wc, int fr, int fq, int tid) const {
;     ...
;         if ((sub & 1) == 0) {
;             const float* bp = bgate + br * 2048 + u.pn * BM + wc * 32 + 8 * fq;
; #pragma unroll
;             for (int ai = 0; ai < 2; ++ai)
; #pragma unroll
;                 for (int bj = 0; bj < 2; ++bj) { const f32x4 b0 = *(const f32x4*)(bp + bj * HALF), b1 = *(const f32x4*)(bp + bj * HALF + 4);
; #pragma unroll
;                     for (int m = 0; m < 4; ++m) { f32x4 v0 = acc[ai][bj][m][0] + b0, v1 = acc[ai][bj][m][1] + b1;
; #pragma unroll
;                         for (int j = 0; j < 4; ++j) { v0[j] = sigmoidf_(v0[j]); v1[j] = sigmoidf_(v1[j]); }
;                         u32x4 w; w.x = cvt_pk_bf16(v0[0], v0[1]); w.y = cvt_pk_bf16(v0[2], v0[3]); w.z = cvt_pk_bf16(v1[0], v1[1]); w.w = cvt_pk_bf16(v1[2], v1[3]);
;                         st_coh16(gp, w); gp += 4096; asm volatile("" : "+v"(gp) :: "memory"); } }
.LBB0_679:
	s_and_b64 vcc, exec, s[12:13]
	s_cbranch_vccz .LBB0_562
	s_lshl_b32 s12, s96, 10
	s_ashr_i32 s13, s12, 31
	s_lshl_b64 s[12:13], s[12:13], 2
	v_readlane_b32 s14, v254, 50
	s_add_u32 s14, s14, s12
	v_readlane_b32 s12, v255, 21
	s_addc_u32 s15, s12, s13
	s_lshl_b32 s12, s97, 8
	s_ashr_i32 s13, s12, 31
	s_lshl_b64 s[12:13], s[12:13], 2
	s_add_u32 s12, s14, s12
	s_addc_u32 s13, s15, s13
	s_lshl_b32 s14, s20, 2
	s_add_u32 s12, s12, s14
	v_lshlrev_b32_e32 v128, 3, v136
	s_addc_u32 s13, s13, 0
	v_ashrrev_i32_e32 v129, 31, v128
	v_lshl_add_u64 v[152:153], v[128:129], 2, s[12:13]
	global_load_dwordx4 v[128:131], v[152:153], off offset:16
	global_load_dwordx4 v[132:135], v[152:153], off
	global_load_dwordx4 v[188:191], v[152:153], off offset:528
	global_load_dwordx4 v[192:195], v[152:153], off offset:512
	global_load_dwordx4 v[196:199], v[152:153], off offset:16
	global_load_dwordx4 v[200:203], v[152:153], off
	s_waitcnt vmcnt(0)
	v_pk_add_f32 v[122:123], v[122:123], v[130:131]
	v_pk_add_f32 v[120:121], v[120:121], v[128:129]
	v_mul_f32_e32 v122, 0xbfb8aa3b, v122
	v_mul_f32_e32 v120, 0xbfb8aa3b, v120
	v_mul_f32_e32 v121, 0xbfb8aa3b, v121
	v_exp_f32_e32 v120, v120
	v_exp_f32_e32 v121, v121
	v_exp_f32_e32 v122, v122
	v_pk_add_f32 v[126:127], v[126:127], v[134:135]
	v_pk_add_f32 v[124:125], v[124:125], v[132:133]
	v_add_f32_e32 v120, 1.0, v120
	v_add_f32_e32 v121, 1.0, v121
	v_add_f32_e32 v122, 1.0, v122
	v_rcp_f32_e32 v136, v120
	v_mul_f32_e32 v120, 0xbfb8aa3b, v125
	v_rcp_f32_e32 v125, v121
	v_mul_f32_e32 v121, 0xbfb8aa3b, v126
	v_rcp_f32_e32 v126, v122
	v_mul_f32_e32 v122, 0xbfb8aa3b, v127
	v_mul_f32_e32 v124, 0xbfb8aa3b, v124
	v_exp_f32_e32 v120, v120
	v_exp_f32_e32 v121, v121
	v_exp_f32_e32 v122, v122
	v_mul_f32_e32 v123, 0xbfb8aa3b, v123
	v_pk_add_f32 v[114:115], v[114:115], v[130:131]
	v_pk_add_f32 v[112:113], v[112:113], v[128:129]
	v_exp_f32_e32 v124, v124
	v_exp_f32_e32 v123, v123
	v_mul_f32_e32 v112, 0xbfb8aa3b, v112
	v_mul_f32_e32 v113, 0xbfb8aa3b, v113
	v_mul_f32_e32 v114, 0xbfb8aa3b, v114
	v_exp_f32_e32 v112, v112
	v_exp_f32_e32 v113, v113
	v_exp_f32_e32 v114, v114
	v_add_f32_e32 v120, 1.0, v120
	v_add_f32_e32 v121, 1.0, v121
	v_add_f32_e32 v122, 1.0, v122
	v_add_f32_e32 v124, 1.0, v124
	v_rcp_f32_e32 v120, v120
	v_rcp_f32_e32 v121, v121
	v_rcp_f32_e32 v122, v122
	v_add_f32_e32 v123, 1.0, v123
	v_rcp_f32_e32 v124, v124
	v_rcp_f32_e32 v123, v123
	v_cvt_pk_bf16_f32 v120, v124, v120
	v_cvt_pk_bf16_f32 v121, v121, v122
	v_cvt_pk_bf16_f32 v122, v136, v125
	v_pk_add_f32 v[118:119], v[118:119], v[134:135]
	v_pk_add_f32 v[116:117], v[116:117], v[132:133]
	v_add_f32_e32 v112, 1.0, v112
	v_add_f32_e32 v113, 1.0, v113
	v_add_f32_e32 v114, 1.0, v114
	v_cvt_pk_bf16_f32 v123, v126, v123
	global_store_dwordx2 v[150:151], v[120:121], off sc1
	global_store_dwordx2 v[150:151], v[122:123], off offset:8 sc1
	v_rcp_f32_e32 v122, v112
	v_mul_f32_e32 v112, 0xbfb8aa3b, v117
	v_rcp_f32_e32 v117, v113
	v_mul_f32_e32 v113, 0xbfb8aa3b, v118
	v_rcp_f32_e32 v118, v114
	v_mul_f32_e32 v114, 0xbfb8aa3b, v119
	v_mul_f32_e32 v116, 0xbfb8aa3b, v116
	v_exp_f32_e32 v112, v112
	v_exp_f32_e32 v113, v113
	v_exp_f32_e32 v114, v114
	v_mul_f32_e32 v115, 0xbfb8aa3b, v115
	v_pk_add_f32 v[106:107], v[106:107], v[130:131]
	v_pk_add_f32 v[104:105], v[104:105], v[128:129]
	v_exp_f32_e32 v116, v116
	v_exp_f32_e32 v115, v115
	v_mul_f32_e32 v104, 0xbfb8aa3b, v104
	v_mul_f32_e32 v105, 0xbfb8aa3b, v105
	v_mul_f32_e32 v106, 0xbfb8aa3b, v106
	v_lshl_add_u64 v[120:121], v[150:151], 0, s[86:87]
	v_exp_f32_e32 v104, v104
	v_exp_f32_e32 v105, v105
	v_exp_f32_e32 v106, v106
	v_add_f32_e32 v112, 1.0, v112
	v_add_f32_e32 v113, 1.0, v113
	v_add_f32_e32 v114, 1.0, v114
	v_add_f32_e32 v116, 1.0, v116
	v_rcp_f32_e32 v112, v112
	v_rcp_f32_e32 v113, v113
	v_rcp_f32_e32 v114, v114
	v_add_f32_e32 v115, 1.0, v115
	v_rcp_f32_e32 v116, v116
	v_rcp_f32_e32 v115, v115
	v_cvt_pk_bf16_f32 v112, v116, v112
	v_cvt_pk_bf16_f32 v113, v113, v114
	v_cvt_pk_bf16_f32 v114, v122, v117
	v_pk_add_f32 v[110:111], v[110:111], v[134:135]
	v_pk_add_f32 v[108:109], v[108:109], v[132:133]
	v_add_f32_e32 v104, 1.0, v104
	v_add_f32_e32 v105, 1.0, v105
	v_add_f32_e32 v106, 1.0, v106
	v_cvt_pk_bf16_f32 v115, v118, v115
	flat_store_dwordx2 v[120:121], v[112:113] sc1
	flat_store_dwordx2 v[120:121], v[114:115] offset:8 sc1
	v_rcp_f32_e32 v114, v104
	v_mul_f32_e32 v104, 0xbfb8aa3b, v109
	v_rcp_f32_e32 v109, v105
	v_mul_f32_e32 v105, 0xbfb8aa3b, v110
	v_rcp_f32_e32 v110, v106
	v_mul_f32_e32 v106, 0xbfb8aa3b, v111
	v_mul_f32_e32 v108, 0xbfb8aa3b, v108
	v_exp_f32_e32 v104, v104
	v_exp_f32_e32 v105, v105
	v_exp_f32_e32 v106, v106
	v_mul_f32_e32 v107, 0xbfb8aa3b, v107
	v_pk_add_f32 v[96:97], v[96:97], v[128:129]
	v_exp_f32_e32 v108, v108
	v_exp_f32_e32 v107, v107
	v_pk_add_f32 v[98:99], v[98:99], v[130:131]
	v_mul_f32_e32 v96, 0xbfb8aa3b, v96
	v_mul_f32_e32 v97, 0xbfb8aa3b, v97
	v_lshl_add_u64 v[112:113], v[120:121], 0, s[86:87]
	v_exp_f32_e32 v96, v96
	v_exp_f32_e32 v97, v97
	v_mul_f32_e32 v98, 0xbfb8aa3b, v98
	v_exp_f32_e32 v98, v98
	v_add_f32_e32 v104, 1.0, v104
	v_add_f32_e32 v105, 1.0, v105
	v_add_f32_e32 v106, 1.0, v106
	v_add_f32_e32 v108, 1.0, v108
	v_rcp_f32_e32 v104, v104
	v_rcp_f32_e32 v105, v105
	v_rcp_f32_e32 v106, v106
	v_add_f32_e32 v107, 1.0, v107
	v_rcp_f32_e32 v108, v108
	v_rcp_f32_e32 v107, v107
	v_cvt_pk_bf16_f32 v104, v108, v104
	v_cvt_pk_bf16_f32 v105, v105, v106
	v_cvt_pk_bf16_f32 v106, v114, v109
	v_pk_add_f32 v[102:103], v[102:103], v[134:135]
	v_pk_add_f32 v[100:101], v[100:101], v[132:133]
	v_add_f32_e32 v96, 1.0, v96
	v_add_f32_e32 v97, 1.0, v97
	v_cvt_pk_bf16_f32 v107, v110, v107
; __device__ __forceinline__ unsigned cvt_pk_bf16(float lo, float hi) { unsigned r; asm("v_cvt_pk_bf16_f32 %0, %1, %2" : "=v"(r) : "v"(lo), "v"(hi)); return r; }
; __device__ __forceinline__ float sigmoidf_(float x) { return __builtin_amdgcn_rcpf(1.0f + __expf(-x)); }
;     __device__ __forceinline__ void operator()(f32x4 (&acc)[2][2][4][2], const GUnit& u, int wr, int wc, int fr, int fq, int tid) const {
;     ...
;                 for (int bj = 0; bj < 2; ++bj) { const f32x4 b0 = *(const f32x4*)(bp + bj * HALF), b1 = *(const f32x4*)(bp + bj * HALF + 4);
; #pragma unroll
;                     for (int m = 0; m < 4; ++m) { f32x4 v0 = acc[ai][bj][m][0] + b0, v1 = acc[ai][bj][m][1] + b1;
; #pragma unroll
;                         for (int j = 0; j < 4; ++j) { v0[j] = sigmoidf_(v0[j]); v1[j] = sigmoidf_(v1[j]); }
;                         u32x4 w; w.x = cvt_pk_bf16(v0[0], v0[1]); w.y = cvt_pk_bf16(v0[2], v0[3]); w.z = cvt_pk_bf16(v1[0], v1[1]); w.w = cvt_pk_bf16(v1[2], v1[3]);
;                         st_coh16(gp, w); gp += 4096; asm volatile("" : "+v"(gp) :: "memory"); } }
	flat_store_dwordx2 v[112:113], v[104:105] sc1
	flat_store_dwordx2 v[112:113], v[106:107] offset:8 sc1
	v_rcp_f32_e32 v106, v96
	v_mul_f32_e32 v96, 0xbfb8aa3b, v101
	v_rcp_f32_e32 v101, v97
	v_mul_f32_e32 v97, 0xbfb8aa3b, v102
	v_add_f32_e32 v98, 1.0, v98
	v_mul_f32_e32 v100, 0xbfb8aa3b, v100
	v_exp_f32_e32 v96, v96
	v_exp_f32_e32 v97, v97
	v_rcp_f32_e32 v102, v98
	v_mul_f32_e32 v98, 0xbfb8aa3b, v103
	v_mul_f32_e32 v99, 0xbfb8aa3b, v99
	v_exp_f32_e32 v100, v100
	v_exp_f32_e32 v98, v98
	v_exp_f32_e32 v99, v99
	v_lshl_add_u64 v[104:105], v[112:113], 0, s[86:87]
	v_add_f32_e32 v96, 1.0, v96
	v_add_f32_e32 v97, 1.0, v97
	v_add_f32_e32 v100, 1.0, v100
	v_rcp_f32_e32 v96, v96
	v_rcp_f32_e32 v97, v97
	v_add_f32_e32 v98, 1.0, v98
	v_add_f32_e32 v99, 1.0, v99
	v_rcp_f32_e32 v100, v100
	v_rcp_f32_e32 v98, v98
	v_rcp_f32_e32 v99, v99
	v_cvt_pk_bf16_f32 v96, v100, v96
	v_cvt_pk_bf16_f32 v97, v97, v98
	v_cvt_pk_bf16_f32 v98, v106, v101
	v_cvt_pk_bf16_f32 v99, v102, v99
	flat_store_dwordx2 v[104:105], v[96:97] sc1
	flat_store_dwordx2 v[104:105], v[98:99] offset:8 sc1
	v_lshl_add_u64 v[104:105], v[104:105], 0, s[86:87]
	s_nop 1
	v_mov_b32_e32 v96, v188
	v_mov_b32_e32 v97, v189
	v_mov_b32_e32 v98, v190
	v_mov_b32_e32 v99, v191
	v_mov_b32_e32 v100, v192
	v_mov_b32_e32 v101, v193
	v_mov_b32_e32 v102, v194
	v_mov_b32_e32 v103, v195
	v_pk_add_f32 v[90:91], v[90:91], v[98:99]
	v_pk_add_f32 v[88:89], v[88:89], v[96:97]
	v_mul_f32_e32 v90, 0xbfb8aa3b, v90
	v_mul_f32_e32 v88, 0xbfb8aa3b, v88
	v_mul_f32_e32 v89, 0xbfb8aa3b, v89
	v_exp_f32_e32 v88, v88
	v_exp_f32_e32 v89, v89
	v_exp_f32_e32 v90, v90
	v_pk_add_f32 v[94:95], v[94:95], v[102:103]
	v_pk_add_f32 v[92:93], v[92:93], v[100:101]
	v_add_f32_e32 v88, 1.0, v88
	v_add_f32_e32 v89, 1.0, v89
	v_add_f32_e32 v90, 1.0, v90
	v_rcp_f32_e32 v106, v88
	v_mul_f32_e32 v88, 0xbfb8aa3b, v93
	v_rcp_f32_e32 v93, v89
	v_mul_f32_e32 v89, 0xbfb8aa3b, v94
	v_rcp_f32_e32 v94, v90
	v_mul_f32_e32 v90, 0xbfb8aa3b, v95
	v_mul_f32_e32 v92, 0xbfb8aa3b, v92
	v_exp_f32_e32 v88, v88
	v_exp_f32_e32 v89, v89
	v_exp_f32_e32 v90, v90
	v_mul_f32_e32 v91, 0xbfb8aa3b, v91
	v_pk_add_f32 v[82:83], v[82:83], v[98:99]
	v_pk_add_f32 v[80:81], v[80:81], v[96:97]
	v_exp_f32_e32 v92, v92
	v_exp_f32_e32 v91, v91
	v_mul_f32_e32 v80, 0xbfb8aa3b, v80
	v_mul_f32_e32 v81, 0xbfb8aa3b, v81
	v_mul_f32_e32 v82, 0xbfb8aa3b, v82
	v_exp_f32_e32 v80, v80
	v_exp_f32_e32 v81, v81
	v_exp_f32_e32 v82, v82
	v_add_f32_e32 v88, 1.0, v88
	v_add_f32_e32 v89, 1.0, v89
	v_add_f32_e32 v90, 1.0, v90
	v_add_f32_e32 v92, 1.0, v92
	v_rcp_f32_e32 v88, v88
	v_rcp_f32_e32 v89, v89
	v_rcp_f32_e32 v90, v90
	v_add_f32_e32 v91, 1.0, v91
	v_rcp_f32_e32 v92, v92
	v_rcp_f32_e32 v91, v91
	v_cvt_pk_bf16_f32 v88, v92, v88
	v_cvt_pk_bf16_f32 v89, v89, v90
	v_cvt_pk_bf16_f32 v90, v106, v93
	v_pk_add_f32 v[86:87], v[86:87], v[102:103]
	v_pk_add_f32 v[84:85], v[84:85], v[100:101]
	v_add_f32_e32 v80, 1.0, v80
	v_add_f32_e32 v81, 1.0, v81
	v_add_f32_e32 v82, 1.0, v82
	v_cvt_pk_bf16_f32 v91, v94, v91
	flat_store_dwordx2 v[104:105], v[88:89] sc1
	flat_store_dwordx2 v[104:105], v[90:91] offset:8 sc1
	v_rcp_f32_e32 v90, v80
	v_mul_f32_e32 v80, 0xbfb8aa3b, v85
	v_rcp_f32_e32 v85, v81
	v_mul_f32_e32 v81, 0xbfb8aa3b, v86
	v_rcp_f32_e32 v86, v82
	v_mul_f32_e32 v82, 0xbfb8aa3b, v87
	v_mul_f32_e32 v84, 0xbfb8aa3b, v84
	v_exp_f32_e32 v80, v80
	v_exp_f32_e32 v81, v81
	v_exp_f32_e32 v82, v82
	v_mul_f32_e32 v83, 0xbfb8aa3b, v83
	v_pk_add_f32 v[74:75], v[74:75], v[98:99]
	v_pk_add_f32 v[72:73], v[72:73], v[96:97]
	v_exp_f32_e32 v84, v84
	v_exp_f32_e32 v83, v83
	v_mul_f32_e32 v72, 0xbfb8aa3b, v72
	v_mul_f32_e32 v73, 0xbfb8aa3b, v73
	v_mul_f32_e32 v74, 0xbfb8aa3b, v74
	v_lshl_add_u64 v[88:89], v[104:105], 0, s[86:87]
	v_exp_f32_e32 v72, v72
	v_exp_f32_e32 v73, v73
	v_exp_f32_e32 v74, v74
	v_add_f32_e32 v80, 1.0, v80
	v_add_f32_e32 v81, 1.0, v81
	v_add_f32_e32 v82, 1.0, v82
	v_add_f32_e32 v84, 1.0, v84
	v_rcp_f32_e32 v80, v80
	v_rcp_f32_e32 v81, v81
	v_rcp_f32_e32 v82, v82
	v_add_f32_e32 v83, 1.0, v83
	v_rcp_f32_e32 v84, v84
	v_rcp_f32_e32 v83, v83
	v_cvt_pk_bf16_f32 v80, v84, v80
	v_cvt_pk_bf16_f32 v81, v81, v82
	v_cvt_pk_bf16_f32 v82, v90, v85
	v_pk_add_f32 v[78:79], v[78:79], v[102:103]
	v_pk_add_f32 v[76:77], v[76:77], v[100:101]
	v_add_f32_e32 v72, 1.0, v72
	v_add_f32_e32 v73, 1.0, v73
	v_add_f32_e32 v74, 1.0, v74
	v_cvt_pk_bf16_f32 v83, v86, v83
	flat_store_dwordx2 v[88:89], v[80:81] sc1
	flat_store_dwordx2 v[88:89], v[82:83] offset:8 sc1
	v_rcp_f32_e32 v82, v72
	v_mul_f32_e32 v72, 0xbfb8aa3b, v77
	v_rcp_f32_e32 v77, v73
	v_mul_f32_e32 v73, 0xbfb8aa3b, v78
	v_rcp_f32_e32 v78, v74
	v_mul_f32_e32 v74, 0xbfb8aa3b, v79
	v_mul_f32_e32 v76, 0xbfb8aa3b, v76
	v_exp_f32_e32 v72, v72
	v_exp_f32_e32 v73, v73
	v_exp_f32_e32 v74, v74
	v_mul_f32_e32 v75, 0xbfb8aa3b, v75
	v_pk_add_f32 v[64:65], v[64:65], v[96:97]
	v_exp_f32_e32 v76, v76
	v_exp_f32_e32 v75, v75
	v_pk_add_f32 v[66:67], v[66:67], v[98:99]
	v_mul_f32_e32 v64, 0xbfb8aa3b, v64
	v_mul_f32_e32 v65, 0xbfb8aa3b, v65
	v_lshl_add_u64 v[80:81], v[88:89], 0, s[86:87]
	v_exp_f32_e32 v64, v64
	v_exp_f32_e32 v65, v65
	v_mul_f32_e32 v66, 0xbfb8aa3b, v66
	v_exp_f32_e32 v66, v66
	v_add_f32_e32 v72, 1.0, v72
	v_add_f32_e32 v73, 1.0, v73
	v_add_f32_e32 v74, 1.0, v74
	v_add_f32_e32 v76, 1.0, v76
	v_rcp_f32_e32 v72, v72
	v_rcp_f32_e32 v73, v73
	v_rcp_f32_e32 v74, v74
	v_add_f32_e32 v75, 1.0, v75
	v_rcp_f32_e32 v76, v76
	v_rcp_f32_e32 v75, v75
	v_cvt_pk_bf16_f32 v72, v76, v72
	v_cvt_pk_bf16_f32 v73, v73, v74
	v_cvt_pk_bf16_f32 v74, v82, v77
	v_pk_add_f32 v[70:71], v[70:71], v[102:103]
	v_pk_add_f32 v[68:69], v[68:69], v[100:101]
	v_add_f32_e32 v64, 1.0, v64
	v_add_f32_e32 v65, 1.0, v65
; __device__ __forceinline__ unsigned cvt_pk_bf16(float lo, float hi) { unsigned r; asm("v_cvt_pk_bf16_f32 %0, %1, %2" : "=v"(r) : "v"(lo), "v"(hi)); return r; }
; __device__ __forceinline__ float sigmoidf_(float x) { return __builtin_amdgcn_rcpf(1.0f + __expf(-x)); }
;     __device__ __forceinline__ void operator()(f32x4 (&acc)[2][2][4][2], const GUnit& u, int wr, int wc, int fr, int fq, int tid) const {
;     ...
;                 for (int bj = 0; bj < 2; ++bj) { const f32x4 b0 = *(const f32x4*)(bp + bj * HALF), b1 = *(const f32x4*)(bp + bj * HALF + 4);
; #pragma unroll
;                     for (int m = 0; m < 4; ++m) { f32x4 v0 = acc[ai][bj][m][0] + b0, v1 = acc[ai][bj][m][1] + b1;
; #pragma unroll
;                         for (int j = 0; j < 4; ++j) { v0[j] = sigmoidf_(v0[j]); v1[j] = sigmoidf_(v1[j]); }
;                         u32x4 w; w.x = cvt_pk_bf16(v0[0], v0[1]); w.y = cvt_pk_bf16(v0[2], v0[3]); w.z = cvt_pk_bf16(v1[0], v1[1]); w.w = cvt_pk_bf16(v1[2], v1[3]);
;                         st_coh16(gp, w); gp += 4096; asm volatile("" : "+v"(gp) :: "memory"); } }
	v_cvt_pk_bf16_f32 v75, v78, v75
	flat_store_dwordx2 v[80:81], v[72:73] sc1
	flat_store_dwordx2 v[80:81], v[74:75] offset:8 sc1
	v_rcp_f32_e32 v74, v64
	v_mul_f32_e32 v64, 0xbfb8aa3b, v69
	v_rcp_f32_e32 v69, v65
	v_mul_f32_e32 v65, 0xbfb8aa3b, v70
	v_add_f32_e32 v66, 1.0, v66
	v_mul_f32_e32 v68, 0xbfb8aa3b, v68
	v_exp_f32_e32 v64, v64
	v_exp_f32_e32 v65, v65
	v_rcp_f32_e32 v70, v66
	v_mul_f32_e32 v66, 0xbfb8aa3b, v71
	v_mul_f32_e32 v67, 0xbfb8aa3b, v67
	v_exp_f32_e32 v68, v68
	v_exp_f32_e32 v66, v66
	v_exp_f32_e32 v67, v67
	v_lshl_add_u64 v[72:73], v[80:81], 0, s[86:87]
	v_add_f32_e32 v64, 1.0, v64
	v_add_f32_e32 v65, 1.0, v65
	v_add_f32_e32 v68, 1.0, v68
	v_rcp_f32_e32 v64, v64
	v_rcp_f32_e32 v65, v65
	v_add_f32_e32 v66, 1.0, v66
	v_add_f32_e32 v67, 1.0, v67
	v_rcp_f32_e32 v68, v68
	v_rcp_f32_e32 v66, v66
	v_rcp_f32_e32 v67, v67
	v_cvt_pk_bf16_f32 v64, v68, v64
	v_cvt_pk_bf16_f32 v65, v65, v66
	v_cvt_pk_bf16_f32 v66, v74, v69
	v_cvt_pk_bf16_f32 v67, v70, v67
	flat_store_dwordx2 v[72:73], v[64:65] sc1
	flat_store_dwordx2 v[72:73], v[66:67] offset:8 sc1
	v_lshl_add_u64 v[72:73], v[72:73], 0, s[86:87]
	s_nop 1
	v_mov_b32_e32 v64, v196
	v_mov_b32_e32 v65, v197
	v_mov_b32_e32 v66, v198
	v_mov_b32_e32 v67, v199
	v_mov_b32_e32 v68, v200
	v_mov_b32_e32 v69, v201
	v_mov_b32_e32 v70, v202
	v_mov_b32_e32 v71, v203
	v_pk_add_f32 v[58:59], v[58:59], v[66:67]
	v_pk_add_f32 v[56:57], v[56:57], v[64:65]
	v_mul_f32_e32 v58, 0xbfb8aa3b, v58
	v_mul_f32_e32 v56, 0xbfb8aa3b, v56
	v_mul_f32_e32 v57, 0xbfb8aa3b, v57
	v_exp_f32_e32 v56, v56
	v_exp_f32_e32 v57, v57
	v_exp_f32_e32 v58, v58
	v_pk_add_f32 v[62:63], v[62:63], v[70:71]
	v_pk_add_f32 v[60:61], v[60:61], v[68:69]
	v_add_f32_e32 v56, 1.0, v56
	v_add_f32_e32 v57, 1.0, v57
	v_add_f32_e32 v58, 1.0, v58
	v_rcp_f32_e32 v74, v56
	v_mul_f32_e32 v56, 0xbfb8aa3b, v61
	v_rcp_f32_e32 v61, v57
	v_mul_f32_e32 v57, 0xbfb8aa3b, v62
	v_rcp_f32_e32 v62, v58
	v_mul_f32_e32 v58, 0xbfb8aa3b, v63
	v_mul_f32_e32 v60, 0xbfb8aa3b, v60
	v_exp_f32_e32 v56, v56
	v_exp_f32_e32 v57, v57
	v_exp_f32_e32 v58, v58
	v_mul_f32_e32 v59, 0xbfb8aa3b, v59
	v_pk_add_f32 v[50:51], v[50:51], v[66:67]
	v_pk_add_f32 v[48:49], v[48:49], v[64:65]
	v_exp_f32_e32 v60, v60
	v_exp_f32_e32 v59, v59
	v_mul_f32_e32 v48, 0xbfb8aa3b, v48
	v_mul_f32_e32 v49, 0xbfb8aa3b, v49
	v_mul_f32_e32 v50, 0xbfb8aa3b, v50
	v_exp_f32_e32 v48, v48
	v_exp_f32_e32 v49, v49
	v_exp_f32_e32 v50, v50
	v_add_f32_e32 v56, 1.0, v56
	v_add_f32_e32 v57, 1.0, v57
	v_add_f32_e32 v58, 1.0, v58
	v_add_f32_e32 v60, 1.0, v60
	v_rcp_f32_e32 v56, v56
	v_rcp_f32_e32 v57, v57
	v_rcp_f32_e32 v58, v58
	v_add_f32_e32 v59, 1.0, v59
	v_rcp_f32_e32 v60, v60
	v_rcp_f32_e32 v59, v59
	v_cvt_pk_bf16_f32 v56, v60, v56
	v_cvt_pk_bf16_f32 v57, v57, v58
	v_cvt_pk_bf16_f32 v58, v74, v61
	v_pk_add_f32 v[54:55], v[54:55], v[70:71]
	v_pk_add_f32 v[52:53], v[52:53], v[68:69]
	v_add_f32_e32 v48, 1.0, v48
	v_add_f32_e32 v49, 1.0, v49
	v_add_f32_e32 v50, 1.0, v50
	v_cvt_pk_bf16_f32 v59, v62, v59
	flat_store_dwordx2 v[72:73], v[56:57] sc1
	flat_store_dwordx2 v[72:73], v[58:59] offset:8 sc1
	v_rcp_f32_e32 v58, v48
	v_mul_f32_e32 v48, 0xbfb8aa3b, v53
	v_rcp_f32_e32 v53, v49
	v_mul_f32_e32 v49, 0xbfb8aa3b, v54
	v_rcp_f32_e32 v54, v50
	v_mul_f32_e32 v50, 0xbfb8aa3b, v55
	v_mul_f32_e32 v52, 0xbfb8aa3b, v52
	v_exp_f32_e32 v48, v48
	v_exp_f32_e32 v49, v49
	v_exp_f32_e32 v50, v50
	v_mul_f32_e32 v51, 0xbfb8aa3b, v51
	v_pk_add_f32 v[42:43], v[42:43], v[66:67]
	v_pk_add_f32 v[40:41], v[40:41], v[64:65]
	v_exp_f32_e32 v52, v52
	v_exp_f32_e32 v51, v51
	v_mul_f32_e32 v40, 0xbfb8aa3b, v40
	v_mul_f32_e32 v41, 0xbfb8aa3b, v41
	v_mul_f32_e32 v42, 0xbfb8aa3b, v42
	v_lshl_add_u64 v[56:57], v[72:73], 0, s[86:87]
	v_exp_f32_e32 v40, v40
	v_exp_f32_e32 v41, v41
	v_exp_f32_e32 v42, v42
	v_add_f32_e32 v48, 1.0, v48
	v_add_f32_e32 v49, 1.0, v49
	v_add_f32_e32 v50, 1.0, v50
	v_add_f32_e32 v52, 1.0, v52
	v_rcp_f32_e32 v48, v48
	v_rcp_f32_e32 v49, v49
	v_rcp_f32_e32 v50, v50
	v_add_f32_e32 v51, 1.0, v51
	v_rcp_f32_e32 v52, v52
	v_rcp_f32_e32 v51, v51
	v_cvt_pk_bf16_f32 v48, v52, v48
	v_cvt_pk_bf16_f32 v49, v49, v50
	v_cvt_pk_bf16_f32 v50, v58, v53
	v_pk_add_f32 v[46:47], v[46:47], v[70:71]
	v_pk_add_f32 v[44:45], v[44:45], v[68:69]
	v_add_f32_e32 v40, 1.0, v40
	v_add_f32_e32 v41, 1.0, v41
	v_add_f32_e32 v42, 1.0, v42
	v_cvt_pk_bf16_f32 v51, v54, v51
	flat_store_dwordx2 v[56:57], v[48:49] sc1
	flat_store_dwordx2 v[56:57], v[50:51] offset:8 sc1
	v_rcp_f32_e32 v50, v40
	v_mul_f32_e32 v40, 0xbfb8aa3b, v45
	v_rcp_f32_e32 v45, v41
	v_mul_f32_e32 v41, 0xbfb8aa3b, v46
	v_rcp_f32_e32 v46, v42
	v_mul_f32_e32 v42, 0xbfb8aa3b, v47
	v_mul_f32_e32 v44, 0xbfb8aa3b, v44
	v_exp_f32_e32 v40, v40
	v_exp_f32_e32 v41, v41
	v_exp_f32_e32 v42, v42
	v_mul_f32_e32 v43, 0xbfb8aa3b, v43
	v_pk_add_f32 v[32:33], v[32:33], v[64:65]
	v_exp_f32_e32 v44, v44
	v_exp_f32_e32 v43, v43
	v_pk_add_f32 v[34:35], v[34:35], v[66:67]
	v_mul_f32_e32 v32, 0xbfb8aa3b, v32
	v_mul_f32_e32 v33, 0xbfb8aa3b, v33
	v_lshl_add_u64 v[48:49], v[56:57], 0, s[86:87]
	v_exp_f32_e32 v32, v32
	v_exp_f32_e32 v33, v33
	v_mul_f32_e32 v34, 0xbfb8aa3b, v34
	v_exp_f32_e32 v34, v34
	v_add_f32_e32 v40, 1.0, v40
	v_add_f32_e32 v41, 1.0, v41
	v_add_f32_e32 v42, 1.0, v42
	v_add_f32_e32 v44, 1.0, v44
	v_rcp_f32_e32 v40, v40
	v_rcp_f32_e32 v41, v41
	v_rcp_f32_e32 v42, v42
	v_add_f32_e32 v43, 1.0, v43
	v_rcp_f32_e32 v44, v44
	v_rcp_f32_e32 v43, v43
	v_cvt_pk_bf16_f32 v40, v44, v40
	v_cvt_pk_bf16_f32 v41, v41, v42
	v_cvt_pk_bf16_f32 v42, v50, v45
	v_pk_add_f32 v[38:39], v[38:39], v[70:71]
	v_pk_add_f32 v[36:37], v[36:37], v[68:69]
	v_add_f32_e32 v32, 1.0, v32
	v_add_f32_e32 v33, 1.0, v33
	v_cvt_pk_bf16_f32 v43, v46, v43
; __device__ __forceinline__ unsigned cvt_pk_bf16(float lo, float hi) { unsigned r; asm("v_cvt_pk_bf16_f32 %0, %1, %2" : "=v"(r) : "v"(lo), "v"(hi)); return r; }
; __device__ __forceinline__ float sigmoidf_(float x) { return __builtin_amdgcn_rcpf(1.0f + __expf(-x)); }
;     __device__ __forceinline__ void operator()(f32x4 (&acc)[2][2][4][2], const GUnit& u, int wr, int wc, int fr, int fq, int tid) const {
;     ...
;                 for (int bj = 0; bj < 2; ++bj) { const f32x4 b0 = *(const f32x4*)(bp + bj * HALF), b1 = *(const f32x4*)(bp + bj * HALF + 4);
; #pragma unroll
;                     for (int m = 0; m < 4; ++m) { f32x4 v0 = acc[ai][bj][m][0] + b0, v1 = acc[ai][bj][m][1] + b1;
; #pragma unroll
;                         for (int j = 0; j < 4; ++j) { v0[j] = sigmoidf_(v0[j]); v1[j] = sigmoidf_(v1[j]); }
;                         u32x4 w; w.x = cvt_pk_bf16(v0[0], v0[1]); w.y = cvt_pk_bf16(v0[2], v0[3]); w.z = cvt_pk_bf16(v1[0], v1[1]); w.w = cvt_pk_bf16(v1[2], v1[3]);
;                         st_coh16(gp, w); gp += 4096; asm volatile("" : "+v"(gp) :: "memory"); } }
	flat_store_dwordx2 v[48:49], v[40:41] sc1
	flat_store_dwordx2 v[48:49], v[42:43] offset:8 sc1
	v_rcp_f32_e32 v42, v32
	v_mul_f32_e32 v32, 0xbfb8aa3b, v37
	v_rcp_f32_e32 v37, v33
	v_mul_f32_e32 v33, 0xbfb8aa3b, v38
	v_add_f32_e32 v34, 1.0, v34
	v_mul_f32_e32 v36, 0xbfb8aa3b, v36
	v_exp_f32_e32 v32, v32
	v_exp_f32_e32 v33, v33
	v_rcp_f32_e32 v38, v34
	v_mul_f32_e32 v34, 0xbfb8aa3b, v39
	v_mul_f32_e32 v35, 0xbfb8aa3b, v35
	v_exp_f32_e32 v36, v36
	v_exp_f32_e32 v34, v34
	v_exp_f32_e32 v35, v35
	v_lshl_add_u64 v[40:41], v[48:49], 0, s[86:87]
	v_add_f32_e32 v32, 1.0, v32
	v_add_f32_e32 v33, 1.0, v33
	v_add_f32_e32 v36, 1.0, v36
	v_rcp_f32_e32 v32, v32
	v_rcp_f32_e32 v33, v33
	v_add_f32_e32 v34, 1.0, v34
	v_add_f32_e32 v35, 1.0, v35
	v_rcp_f32_e32 v36, v36
	v_rcp_f32_e32 v34, v34
	v_rcp_f32_e32 v35, v35
	v_cvt_pk_bf16_f32 v32, v36, v32
	v_cvt_pk_bf16_f32 v33, v33, v34
	v_cvt_pk_bf16_f32 v34, v42, v37
	v_cvt_pk_bf16_f32 v35, v38, v35
	flat_store_dwordx2 v[40:41], v[32:33] sc1
	flat_store_dwordx2 v[40:41], v[34:35] offset:8 sc1
	v_lshl_add_u64 v[40:41], v[40:41], 0, s[86:87]
	s_nop 1
	v_mov_b32_e32 v32, v188
	v_mov_b32_e32 v33, v189
	v_mov_b32_e32 v34, v190
	v_mov_b32_e32 v35, v191
	v_mov_b32_e32 v36, v192
	v_mov_b32_e32 v37, v193
	v_mov_b32_e32 v38, v194
	v_mov_b32_e32 v39, v195
	v_pk_add_f32 v[26:27], v[26:27], v[34:35]
	v_pk_add_f32 v[24:25], v[24:25], v[32:33]
	v_mul_f32_e32 v26, 0xbfb8aa3b, v26
	v_mul_f32_e32 v24, 0xbfb8aa3b, v24
	v_mul_f32_e32 v25, 0xbfb8aa3b, v25
	v_exp_f32_e32 v24, v24
	v_exp_f32_e32 v25, v25
	v_exp_f32_e32 v26, v26
	v_pk_add_f32 v[30:31], v[30:31], v[38:39]
	v_pk_add_f32 v[28:29], v[28:29], v[36:37]
	v_add_f32_e32 v24, 1.0, v24
	v_add_f32_e32 v25, 1.0, v25
	v_add_f32_e32 v26, 1.0, v26
	v_rcp_f32_e32 v42, v24
	v_mul_f32_e32 v24, 0xbfb8aa3b, v29
	v_rcp_f32_e32 v29, v25
	v_mul_f32_e32 v25, 0xbfb8aa3b, v30
	v_rcp_f32_e32 v30, v26
	v_mul_f32_e32 v26, 0xbfb8aa3b, v31
	v_mul_f32_e32 v28, 0xbfb8aa3b, v28
	v_exp_f32_e32 v24, v24
	v_exp_f32_e32 v25, v25
	v_exp_f32_e32 v26, v26
	v_mul_f32_e32 v27, 0xbfb8aa3b, v27
	v_pk_add_f32 v[18:19], v[18:19], v[34:35]
	v_pk_add_f32 v[16:17], v[16:17], v[32:33]
	v_exp_f32_e32 v28, v28
	v_exp_f32_e32 v27, v27
	v_mul_f32_e32 v16, 0xbfb8aa3b, v16
	v_mul_f32_e32 v17, 0xbfb8aa3b, v17
	v_mul_f32_e32 v18, 0xbfb8aa3b, v18
	v_exp_f32_e32 v16, v16
	v_exp_f32_e32 v17, v17
	v_exp_f32_e32 v18, v18
	v_add_f32_e32 v24, 1.0, v24
	v_add_f32_e32 v25, 1.0, v25
	v_add_f32_e32 v26, 1.0, v26
	v_add_f32_e32 v28, 1.0, v28
	v_rcp_f32_e32 v24, v24
	v_rcp_f32_e32 v25, v25
	v_rcp_f32_e32 v26, v26
	v_add_f32_e32 v27, 1.0, v27
	v_rcp_f32_e32 v28, v28
	v_rcp_f32_e32 v27, v27
	v_cvt_pk_bf16_f32 v24, v28, v24
	v_cvt_pk_bf16_f32 v25, v25, v26
	v_cvt_pk_bf16_f32 v26, v42, v29
	v_pk_add_f32 v[22:23], v[22:23], v[38:39]
	v_pk_add_f32 v[20:21], v[20:21], v[36:37]
	v_add_f32_e32 v16, 1.0, v16
	v_add_f32_e32 v17, 1.0, v17
	v_add_f32_e32 v18, 1.0, v18
	v_cvt_pk_bf16_f32 v27, v30, v27
	flat_store_dwordx2 v[40:41], v[24:25] sc1
	flat_store_dwordx2 v[40:41], v[26:27] offset:8 sc1
	v_rcp_f32_e32 v26, v16
	v_mul_f32_e32 v16, 0xbfb8aa3b, v21
	v_rcp_f32_e32 v21, v17
	v_mul_f32_e32 v17, 0xbfb8aa3b, v22
	v_rcp_f32_e32 v22, v18
	v_mul_f32_e32 v18, 0xbfb8aa3b, v23
	v_mul_f32_e32 v20, 0xbfb8aa3b, v20
	v_exp_f32_e32 v16, v16
	v_exp_f32_e32 v17, v17
	v_exp_f32_e32 v18, v18
	v_mul_f32_e32 v19, 0xbfb8aa3b, v19
	v_pk_add_f32 v[10:11], v[10:11], v[34:35]
	v_pk_add_f32 v[8:9], v[8:9], v[32:33]
	v_exp_f32_e32 v20, v20
	v_exp_f32_e32 v19, v19
	v_mul_f32_e32 v8, 0xbfb8aa3b, v8
	v_mul_f32_e32 v9, 0xbfb8aa3b, v9
	v_mul_f32_e32 v10, 0xbfb8aa3b, v10
	v_lshl_add_u64 v[24:25], v[40:41], 0, s[86:87]
	v_exp_f32_e32 v8, v8
	v_exp_f32_e32 v9, v9
	v_exp_f32_e32 v10, v10
	v_add_f32_e32 v16, 1.0, v16
	v_add_f32_e32 v17, 1.0, v17
	v_add_f32_e32 v18, 1.0, v18
	v_add_f32_e32 v20, 1.0, v20
	v_rcp_f32_e32 v16, v16
	v_rcp_f32_e32 v17, v17
	v_rcp_f32_e32 v18, v18
	v_add_f32_e32 v19, 1.0, v19
	v_rcp_f32_e32 v20, v20
	v_rcp_f32_e32 v19, v19
	v_cvt_pk_bf16_f32 v16, v20, v16
	v_cvt_pk_bf16_f32 v17, v17, v18
	v_cvt_pk_bf16_f32 v18, v26, v21
	v_pk_add_f32 v[14:15], v[14:15], v[38:39]
	v_pk_add_f32 v[12:13], v[12:13], v[36:37]
	v_add_f32_e32 v8, 1.0, v8
	v_add_f32_e32 v9, 1.0, v9
	v_add_f32_e32 v10, 1.0, v10
	v_cvt_pk_bf16_f32 v19, v22, v19
	flat_store_dwordx2 v[24:25], v[16:17] sc1
	flat_store_dwordx2 v[24:25], v[18:19] offset:8 sc1
	v_rcp_f32_e32 v18, v8
	v_mul_f32_e32 v8, 0xbfb8aa3b, v13
	v_rcp_f32_e32 v13, v9
	v_mul_f32_e32 v9, 0xbfb8aa3b, v14
	v_rcp_f32_e32 v14, v10
	v_mul_f32_e32 v10, 0xbfb8aa3b, v15
	v_mul_f32_e32 v12, 0xbfb8aa3b, v12
	v_exp_f32_e32 v8, v8
	v_exp_f32_e32 v9, v9
	v_exp_f32_e32 v10, v10
	v_mul_f32_e32 v11, 0xbfb8aa3b, v11
	v_pk_add_f32 v[0:1], v[0:1], v[32:33]
	v_exp_f32_e32 v12, v12
	v_exp_f32_e32 v11, v11
	v_pk_add_f32 v[2:3], v[2:3], v[34:35]
	v_mul_f32_e32 v0, 0xbfb8aa3b, v0
	v_mul_f32_e32 v1, 0xbfb8aa3b, v1
	v_lshl_add_u64 v[16:17], v[24:25], 0, s[86:87]
	v_exp_f32_e32 v0, v0
	v_exp_f32_e32 v1, v1
	v_mul_f32_e32 v2, 0xbfb8aa3b, v2
	v_exp_f32_e32 v2, v2
	v_add_f32_e32 v8, 1.0, v8
	v_add_f32_e32 v9, 1.0, v9
	v_add_f32_e32 v10, 1.0, v10
	v_add_f32_e32 v12, 1.0, v12
	v_rcp_f32_e32 v8, v8
	v_rcp_f32_e32 v9, v9
	v_rcp_f32_e32 v10, v10
	v_add_f32_e32 v11, 1.0, v11
	v_rcp_f32_e32 v12, v12
	v_rcp_f32_e32 v11, v11
	v_cvt_pk_bf16_f32 v8, v12, v8
	v_cvt_pk_bf16_f32 v9, v9, v10
	v_cvt_pk_bf16_f32 v10, v18, v13
	v_pk_add_f32 v[6:7], v[6:7], v[38:39]
	v_pk_add_f32 v[4:5], v[4:5], v[36:37]
	v_add_f32_e32 v0, 1.0, v0
	v_add_f32_e32 v1, 1.0, v1
	v_cvt_pk_bf16_f32 v11, v14, v11
	flat_store_dwordx2 v[16:17], v[8:9] sc1
	flat_store_dwordx2 v[16:17], v[10:11] offset:8 sc1
	v_rcp_f32_e32 v10, v0
	v_mul_f32_e32 v0, 0xbfb8aa3b, v5
	v_rcp_f32_e32 v5, v1
	v_mul_f32_e32 v1, 0xbfb8aa3b, v6
	v_add_f32_e32 v2, 1.0, v2
	v_mul_f32_e32 v4, 0xbfb8aa3b, v4
	v_exp_f32_e32 v0, v0
	v_exp_f32_e32 v1, v1
	v_rcp_f32_e32 v6, v2
	v_mul_f32_e32 v2, 0xbfb8aa3b, v7
	v_mul_f32_e32 v3, 0xbfb8aa3b, v3
	v_exp_f32_e32 v4, v4
	v_exp_f32_e32 v2, v2
	v_exp_f32_e32 v3, v3
	v_lshl_add_u64 v[8:9], v[16:17], 0, s[86:87]
	v_add_f32_e32 v0, 1.0, v0
	v_add_f32_e32 v1, 1.0, v1
	v_add_f32_e32 v4, 1.0, v4
	v_rcp_f32_e32 v0, v0
	v_rcp_f32_e32 v1, v1
	v_add_f32_e32 v2, 1.0, v2
	v_add_f32_e32 v3, 1.0, v3
	v_rcp_f32_e32 v4, v4
	v_rcp_f32_e32 v2, v2
	v_rcp_f32_e32 v3, v3
	v_cvt_pk_bf16_f32 v0, v4, v0
	v_cvt_pk_bf16_f32 v1, v1, v2
	v_cvt_pk_bf16_f32 v2, v10, v5
	v_cvt_pk_bf16_f32 v3, v6, v3
	flat_store_dwordx2 v[8:9], v[0:1] sc1
	flat_store_dwordx2 v[8:9], v[2:3] offset:8 sc1
	v_lshl_add_u64 v[0:1], v[8:9], 0, s[86:87]
	s_branch .LBB0_562
